# G1 even+odd K-loop LDS-DMA rebalance 2/6 -> 4/4 per superphase
# speedup vs baseline: 1.0070x; 1.0070x over previous
; #define PG8_STAGE(bufoff, gbase, voff) do { _Pragma("unroll") for (int _i = 0; _i < 2; ++_i) \
;         __builtin_amdgcn_global_load_lds((const unsigned*)((const char*)(gbase) + (voff)[_i]), (PG8_LAS unsigned*)(lds + (bufoff) + ldsw + _i * 8192), 16, 0, 0); } while (0)
; #define PG8_WAIT_V(n) asm volatile("s_waitcnt vmcnt(" #n ")" ::: "memory")
; #define PG8_BAR __builtin_amdgcn_s_barrier()
; #define LAS __attribute__((address_space(3)))
; template <class Epi, class Sched, bool ALIGN_EPI = false, bool SP2 = false>
; __device__ __forceinline__ void gemm_phase(PG8_LAS unsigned char* lds, const Gemm g, const Sched& S, const Epi& E, const int wave_id) {
;     ...
;         PG8_STAGE(PG8_SB(0, 0), cB, voffB); PG8_STAGE(PG8_SB(0, 1), cB + hstep, voffB); PG8_STAGE(PG8_SA(0, 0), cA, voffA); PG8_STAGE(PG8_SA(0, 1), cA + hstep, voffA);
;         if (wr == 1) PG8_BAR;
;         PG8_WAIT_V(2); PG8_BAR;
;         PG8_STAGE(PG8_SB(1, 0), cB + kstep, voffB); PG8_STAGE(PG8_SA(1, 0), cA + kstep, voffA); PG8_STAGE(PG8_SB(1, 1), cB + hstep + kstep, voffB);
;         PG8_WAIT_V(6); PG8_BAR;
;     __device__ __forceinline__ void pre_finish(const f32x4 (&p)[4], const float (&c)[3], int tid) const {
;         if (tid < 256) { const f32x4 s4 = (p[0] + p[1]) + (p[2] + p[3]); ((LAS float*)rtab)[tid] = rsqrtf(((s4[0] + s4[1]) + (s4[2] + s4[3])) * (1.0f / D) + EPS); }
.LBB0_683:
	v_mov_b32_e32 v147, v201
	v_lshl_add_u64 v[26:27], s[14:15], 0, v[146:147]
	v_mov_b32_e32 v151, v201
	v_lshl_add_u64 v[28:29], s[14:15], 0, v[150:151]
	v_mov_b32_e32 v145, v201
	s_add_i32 m0, s84, 0x18000
	v_lshl_add_u64 v[26:27], v[26:27], 0, s[88:89]
	s_waitcnt vmcnt(0)
	v_lshl_add_u64 v[30:31], s[12:13], 0, v[144:145]
	v_mov_b32_e32 v149, v201
	s_waitcnt vmcnt(2)
	s_barrier
	global_load_lds_dwordx4 v[26:27], off
	v_lshl_add_u64 v[26:27], v[28:29], 0, s[88:89]
	s_add_i32 m0, s84, 0x1a000
	s_add_i32 s90, s84, 0x8000
	s_add_i32 s92, s84, 0xa000
	v_lshl_add_u64 v[32:33], s[12:13], 0, v[148:149]
	global_load_lds_dwordx4 v[26:27], off
	s_add_u32 s4, s14, 0x40080
	s_addc_u32 s5, s15, 0
	s_add_i32 m0, s84, 0x1c000
	v_lshl_add_u64 v[26:27], s[4:5], 0, v[146:147]
	global_load_lds_dwordx4 v[26:27], off
	v_lshl_add_u64 v[26:27], s[4:5], 0, v[150:151]
	s_add_i32 m0, s84, 0x1e000
	s_nop 0
	global_load_lds_dwordx4 v[26:27], off
	s_waitcnt vmcnt(4)
	s_barrier
	s_and_saveexec_b64 s[8:9], vcc
	s_cbranch_execz .LBB0_685
	v_pk_add_f32 v[8:9], v[8:9], v[12:13]
	v_pk_add_f32 v[10:11], v[10:11], v[14:15]
	v_pk_add_f32 v[0:1], v[0:1], v[4:5]
	v_pk_add_f32 v[2:3], v[2:3], v[6:7]
	v_pk_add_f32 v[0:1], v[0:1], v[8:9]
	v_pk_add_f32 v[2:3], v[2:3], v[10:11]
	s_mov_b32 s1, 0x800000
	v_pk_mov_b32 v[4:5], v[0:1], v[2:3] op_sel:[1,0]
	v_mov_b32_e32 v1, v3
	v_pk_add_f32 v[0:1], v[4:5], v[0:1]
	s_nop 0
	v_add_f32_e32 v0, v0, v1
	v_mov_b32_e32 v1, 0x358637bd
	v_fmamk_f32 v0, v0, 0x3a800000, v1
	v_mul_f32_e32 v1, 0x4b800000, v0
	v_cmp_gt_f32_e32 vcc, s1, v0
	s_nop 1
	v_cndmask_b32_e32 v0, v0, v1, vcc
	v_rsq_f32_e32 v0, v0
	s_nop 0
	v_mul_f32_e32 v1, 0x45800000, v0
	v_cndmask_b32_e32 v0, v0, v1, vcc
	v_lshl_add_u32 v1, v16, 2, 0
	v_add_u32_e32 v1, 0x22400, v1
	ds_write_b32 v1, v0

; #define PG8_STAGE(bufoff, gbase, voff) do { _Pragma("unroll") for (int _i = 0; _i < 2; ++_i) \
;         __builtin_amdgcn_global_load_lds((const unsigned*)((const char*)(gbase) + (voff)[_i]), (PG8_LAS unsigned*)(lds + (bufoff) + ldsw + _i * 8192), 16, 0, 0); } while (0)
; #define PG8_LDA(dst, b, h) do { _Pragma("unroll") for (int m = 0; m < 4; ++m) _Pragma("unroll") for (int k = 0; k < 2; ++k) dst[m][k] = *(const PG8_LAS bf16x8*)(lds + PG8_SA(b, h) + aoff + m * 2048 + k * 1024); } while (0)
; #define PG8_LDB(dst, b, h) do { _Pragma("unroll") for (int n = 0; n < 2; ++n) _Pragma("unroll") for (int k = 0; k < 2; ++k) dst[n][k] = *(const PG8_LAS bf16x8*)(lds + PG8_SB(b, h) + boff + n * 2048 + k * 1024); } while (0)
; #define PG8_MMA(ai, bj, At, Bt) do { __builtin_amdgcn_s_setprio(1); _Pragma("unroll") for (int m = 0; m < 4; ++m) _Pragma("unroll") for (int n = 0; n < 2; ++n) _Pragma("unroll") for (int k = 0; k < 2; ++k) \
;         acc[ai][bj][m][n] = __builtin_amdgcn_mfma_f32_16x16x32_bf16(Bt[n][k], At[m][k], acc[ai][bj][m][n], 0, 0, 0); __builtin_amdgcn_s_setprio(0); } while (0)
; #define PG8_WAIT_V(n) asm volatile("s_waitcnt vmcnt(" #n ")" ::: "memory")
; #define PG8_BAR __builtin_amdgcn_s_barrier()
; template <class Epi, class Sched, bool ALIGN_EPI = false, bool SP2 = false>
; __device__ __forceinline__ void gemm_phase(PG8_LAS unsigned char* lds, const Gemm g, const Sched& S, const Epi& E, const int wave_id) {
;     ...
;         for (int t = 0; t < nt; t += 2) {
;             const bool last = (t == nt - 2);
;             const char* a1 = cA + (size_t)(t + 1) * kstep;
;             const char* a2 = last ? nA : cA + (size_t)(t + 2) * kstep; const char* b2 = last ? nB : cB + (size_t)(t + 2) * kstep;
;             const char* a3 = a2 + kstep; const char* b3 = b2 + kstep;
;             if (last && has_next) S.a_ready(nxt);
;             if constexpr (SP2) {
;             PG8_LDB(B0, 0, 0); PG8_LDB(B1, 0, 1); PG8_SCHED; PG8_LDA(At, 0, 0); PG8_STAGE(PG8_SA(1, 1), a1 + hstep, voffA);
;             PG8_WAIT_V(8); PG8_WAIT_L(0); PG8_BAR; PG8_MMA(0, 0, At, B0); PG8_MMA(0, 1, At, B1); PG8_BAR; PG8_SCHED;
;             PG8_LDA(At, 0, 1); PG8_STAGE(PG8_SB(0, 0), b2, voffB); PG8_STAGE(PG8_SB(0, 1), b2 + hstep, voffB); PG8_STAGE(PG8_SA(0, 0), a2, voffA);
;             PG8_WAIT_V(8); PG8_WAIT_L(0); PG8_BAR; PG8_MMA(1, 0, At, B0); PG8_MMA(1, 1, At, B1); PG8_BAR; PG8_SCHED;
.LBB0_695:
	s_add_u32 s14, s12, 0xfffc0080
	s_addc_u32 s15, s13, -1
	s_add_i32 s73, 0, 0x10000
	s_cmp_eq_u32 s72, 12
	s_cselect_b32 s17, s11, s15
	s_cselect_b32 s16, s61, s14
	s_cselect_b32 s15, s59, s69
	s_cselect_b32 s14, s67, s68
	s_add_i32 s34, 0, 0x14000
	v_add_u32_e32 v156, s73, v168
	v_add_u32_e32 v164, s34, v168
	ds_read_b128 v[32:35], v156
	ds_read_b128 v[36:39], v156 offset:1024
	ds_read_b128 v[40:43], v156 offset:2048
	ds_read_b128 v[156:159], v156 offset:3072
	ds_read_b128 v[160:163], v164
	ds_read_b128 v[170:173], v164 offset:1024
	ds_read_b128 v[174:177], v164 offset:2048
	ds_read_b128 v[178:181], v164 offset:3072
	ds_read_b128 v[182:185], v169
	ds_read_b128 v[186:189], v169 offset:1024
	ds_read_b128 v[190:193], v169 offset:2048
	ds_read_b128 v[194:197], v169 offset:3072
	ds_read_b128 v[202:205], v169 offset:4096
	ds_read_b128 v[206:209], v169 offset:5120
	ds_read_b128 v[212:215], v169 offset:6144
	ds_read_b128 v[216:219], v169 offset:7168
	s_add_u32 vcc_lo, s12, 0xfffc0000
	s_addc_u32 vcc_hi, s13, -1
	v_lshl_add_u64 v[164:165], vcc, 0, v[152:153]
	s_mov_b32 m0, s90
	s_nop 0
	global_load_lds_dwordx4 v[164:165], off
	v_lshl_add_u64 v[164:165], vcc, 0, v[154:155]
	s_mov_b32 m0, s92
	s_nop 0
	global_load_lds_dwordx4 v[164:165], off
	v_lshl_add_u64 v[164:165], s[12:13], 0, v[152:153]
	s_add_i32 m0, s84, 0xc000
	s_nop 0
	global_load_lds_dwordx4 v[164:165], off
	v_lshl_add_u64 v[164:165], s[12:13], 0, v[154:155]
	s_add_i32 m0, s84, 0xe000
	s_nop 0
	global_load_lds_dwordx4 v[164:165], off
	s_waitcnt vmcnt(8)
	s_waitcnt lgkmcnt(0)
	s_barrier
	s_setprio 1
	s_waitcnt lgkmcnt(0)
	v_mfma_f32_16x16x32_bf16 v[136:139], v[32:35], v[182:185], v[136:139]
	v_mfma_f32_16x16x32_bf16 v[132:135], v[40:43], v[182:185], v[132:135]
	v_mfma_f32_16x16x32_bf16 v[128:131], v[32:35], v[190:193], v[128:131]
	v_mfma_f32_16x16x32_bf16 v[124:127], v[40:43], v[190:193], v[124:127]
	v_mfma_f32_16x16x32_bf16 v[120:123], v[32:35], v[202:205], v[120:123]
	v_mfma_f32_16x16x32_bf16 v[116:119], v[40:43], v[202:205], v[116:119]
	v_mfma_f32_16x16x32_bf16 v[112:115], v[32:35], v[212:215], v[112:115]
	v_mfma_f32_16x16x32_bf16 v[104:107], v[40:43], v[212:215], v[104:107]
	v_mfma_f32_16x16x32_bf16 v[136:139], v[36:39], v[186:189], v[136:139]
	v_mfma_f32_16x16x32_bf16 v[132:135], v[156:159], v[186:189], v[132:135]
	v_mfma_f32_16x16x32_bf16 v[128:131], v[36:39], v[194:197], v[128:131]
	v_mfma_f32_16x16x32_bf16 v[124:127], v[156:159], v[194:197], v[124:127]
	v_mfma_f32_16x16x32_bf16 v[120:123], v[36:39], v[206:209], v[120:123]
	v_mfma_f32_16x16x32_bf16 v[116:119], v[156:159], v[206:209], v[116:119]
	v_mfma_f32_16x16x32_bf16 v[112:115], v[36:39], v[216:219], v[112:115]
	v_mfma_f32_16x16x32_bf16 v[104:107], v[156:159], v[216:219], v[104:107]
	s_setprio 0
	s_setprio 1
	v_mfma_f32_16x16x32_bf16 v[80:83], v[160:163], v[182:185], v[80:83]
	v_mfma_f32_16x16x32_bf16 v[76:79], v[174:177], v[182:185], v[76:79]
	v_mfma_f32_16x16x32_bf16 v[64:67], v[160:163], v[190:193], v[64:67]
	v_mfma_f32_16x16x32_bf16 v[60:63], v[174:177], v[190:193], v[60:63]
	v_mfma_f32_16x16x32_bf16 v[56:59], v[160:163], v[202:205], v[56:59]
	v_mfma_f32_16x16x32_bf16 v[52:55], v[174:177], v[202:205], v[52:55]
	v_mfma_f32_16x16x32_bf16 v[48:51], v[160:163], v[212:215], v[48:51]
	v_mfma_f32_16x16x32_bf16 v[44:47], v[174:177], v[212:215], v[44:47]
	v_mfma_f32_16x16x32_bf16 v[80:83], v[170:173], v[186:189], v[80:83]
	v_mfma_f32_16x16x32_bf16 v[76:79], v[178:181], v[186:189], v[76:79]
	v_mfma_f32_16x16x32_bf16 v[64:67], v[170:173], v[194:197], v[64:67]
	v_mfma_f32_16x16x32_bf16 v[60:63], v[178:181], v[194:197], v[60:63]
	v_mfma_f32_16x16x32_bf16 v[56:59], v[170:173], v[206:209], v[56:59]
	v_mfma_f32_16x16x32_bf16 v[52:55], v[178:181], v[206:209], v[52:55]
	v_mfma_f32_16x16x32_bf16 v[48:51], v[170:173], v[216:219], v[48:51]
	v_mfma_f32_16x16x32_bf16 v[44:47], v[178:181], v[216:219], v[44:47]
	s_setprio 0
	s_barrier
	s_add_i32 s73, s73, s25
	v_lshl_add_u64 v[164:165], s[14:15], 0, v[146:147]
	s_mov_b32 m0, s73
	ds_read_b128 v[182:185], v169 offset:16384
	ds_read_b128 v[186:189], v169 offset:17408
	ds_read_b128 v[190:193], v169 offset:18432
	ds_read_b128 v[194:197], v169 offset:19456
	ds_read_b128 v[202:205], v169 offset:20480
	ds_read_b128 v[206:209], v169 offset:21504
	ds_read_b128 v[212:215], v169 offset:22528
	ds_read_b128 v[216:219], v169 offset:23552
	global_load_lds_dwordx4 v[164:165], off
	s_add_i32 m0, s73, 0x2000
	s_add_u32 vcc_lo, s14, 0x40000
	v_lshl_add_u64 v[198:199], s[14:15], 0, v[150:151]
	s_addc_u32 vcc_hi, s15, 0
	s_add_i32 s34, s34, s25
	global_load_lds_dwordx4 v[198:199], off
	v_lshl_add_u64 v[210:211], vcc, 0, v[146:147]
	s_mov_b32 m0, s34
	v_lshl_add_u64 v[224:225], s[16:17], 0, v[148:149]
	global_load_lds_dwordx4 v[210:211], off
	v_lshl_add_u64 v[210:211], vcc, 0, v[150:151]
	s_add_i32 m0, s34, 0x2000
	s_nop 0
	global_load_lds_dwordx4 v[210:211], off
	v_lshl_add_u64 v[210:211], s[16:17], 0, v[144:145]
	s_waitcnt vmcnt(6)
	s_waitcnt lgkmcnt(0)
	s_barrier
; #define PG8_STAGE(bufoff, gbase, voff) do { _Pragma("unroll") for (int _i = 0; _i < 2; ++_i) \
;         __builtin_amdgcn_global_load_lds((const unsigned*)((const char*)(gbase) + (voff)[_i]), (PG8_LAS unsigned*)(lds + (bufoff) + ldsw + _i * 8192), 16, 0, 0); } while (0)
; #define PG8_LDA(dst, b, h) do { _Pragma("unroll") for (int m = 0; m < 4; ++m) _Pragma("unroll") for (int k = 0; k < 2; ++k) dst[m][k] = *(const PG8_LAS bf16x8*)(lds + PG8_SA(b, h) + aoff + m * 2048 + k * 1024); } while (0)
; #define PG8_LDB(dst, b, h) do { _Pragma("unroll") for (int n = 0; n < 2; ++n) _Pragma("unroll") for (int k = 0; k < 2; ++k) dst[n][k] = *(const PG8_LAS bf16x8*)(lds + PG8_SB(b, h) + boff + n * 2048 + k * 1024); } while (0)
; #define PG8_MMA(ai, bj, At, Bt) do { __builtin_amdgcn_s_setprio(1); _Pragma("unroll") for (int m = 0; m < 4; ++m) _Pragma("unroll") for (int n = 0; n < 2; ++n) _Pragma("unroll") for (int k = 0; k < 2; ++k) \
;         acc[ai][bj][m][n] = __builtin_amdgcn_mfma_f32_16x16x32_bf16(Bt[n][k], At[m][k], acc[ai][bj][m][n], 0, 0, 0); __builtin_amdgcn_s_setprio(0); } while (0)
; #define PG8_WAIT_V(n) asm volatile("s_waitcnt vmcnt(" #n ")" ::: "memory")
; #define PG8_WAIT_L(n) asm volatile("s_waitcnt lgkmcnt(" #n ")" ::: "memory")
; #define PG8_BAR __builtin_amdgcn_s_barrier()
; #define PG8_SCHED __builtin_amdgcn_sched_barrier(0)
; template <class Epi, class Sched, bool ALIGN_EPI = false, bool SP2 = false>
; __device__ __forceinline__ void gemm_phase(PG8_LAS unsigned char* lds, const Gemm g, const Sched& S, const Epi& E, const int wave_id) {
;     ...
;             PG8_WAIT_V(8); PG8_WAIT_L(0); PG8_BAR; PG8_MMA(0, 0, At, B0); PG8_MMA(0, 1, At, B1); PG8_BAR; PG8_SCHED;
;             PG8_LDA(At, 0, 1); PG8_STAGE(PG8_SB(0, 0), b2, voffB); PG8_STAGE(PG8_SB(0, 1), b2 + hstep, voffB); PG8_STAGE(PG8_SA(0, 0), a2, voffA);
;             PG8_WAIT_V(8); PG8_WAIT_L(0); PG8_BAR; PG8_MMA(1, 0, At, B0); PG8_MMA(1, 1, At, B1); PG8_BAR; PG8_SCHED;
;             PG8_LDB(B0, 1, 0); PG8_LDB(B1, 1, 1); PG8_SCHED; PG8_LDA(At, 1, 0); PG8_STAGE(PG8_SA(0, 1), a2 + hstep, voffA);
;             PG8_WAIT_V(8); PG8_WAIT_L(0); PG8_BAR; PG8_MMA(0, 0, At, B0); PG8_MMA(0, 1, At, B1); PG8_BAR; PG8_SCHED;
	s_setprio 1
	s_waitcnt lgkmcnt(0)
	v_mfma_f32_16x16x32_bf16 v[108:111], v[32:35], v[182:185], v[108:111]
	v_mfma_f32_16x16x32_bf16 v[96:99], v[40:43], v[182:185], v[96:99]
	v_mfma_f32_16x16x32_bf16 v[100:103], v[32:35], v[190:193], v[100:103]
	v_mfma_f32_16x16x32_bf16 v[88:91], v[40:43], v[190:193], v[88:91]
	v_mfma_f32_16x16x32_bf16 v[92:95], v[32:35], v[202:205], v[92:95]
	v_mfma_f32_16x16x32_bf16 v[72:75], v[40:43], v[202:205], v[72:75]
	v_mfma_f32_16x16x32_bf16 v[32:35], v[32:35], v[212:215], v[84:87]
	v_mfma_f32_16x16x32_bf16 v[108:111], v[36:39], v[186:189], v[108:111]
	v_mfma_f32_16x16x32_bf16 v[96:99], v[156:159], v[186:189], v[96:99]
	v_mfma_f32_16x16x32_bf16 v[100:103], v[36:39], v[194:197], v[100:103]
	v_mfma_f32_16x16x32_bf16 v[88:91], v[156:159], v[194:197], v[88:91]
	v_mfma_f32_16x16x32_bf16 v[92:95], v[36:39], v[206:209], v[92:95]
	v_mfma_f32_16x16x32_bf16 v[72:75], v[156:159], v[206:209], v[72:75]
	v_mfma_f32_16x16x32_bf16 v[32:35], v[36:39], v[216:219], v[32:35]
	v_mfma_f32_16x16x32_bf16 v[36:39], v[40:43], v[212:215], v[68:71]
	v_mfma_f32_16x16x32_bf16 v[36:39], v[156:159], v[216:219], v[36:39]
	s_setprio 0
	s_setprio 1
	v_mfma_f32_16x16x32_bf16 v[28:31], v[160:163], v[182:185], v[28:31]
	v_mfma_f32_16x16x32_bf16 v[24:27], v[174:177], v[182:185], v[24:27]
	v_mfma_f32_16x16x32_bf16 v[20:23], v[160:163], v[190:193], v[20:23]
	v_mfma_f32_16x16x32_bf16 v[16:19], v[174:177], v[190:193], v[16:19]
	v_mfma_f32_16x16x32_bf16 v[12:15], v[160:163], v[202:205], v[12:15]
	v_mfma_f32_16x16x32_bf16 v[8:11], v[174:177], v[202:205], v[8:11]
	v_mfma_f32_16x16x32_bf16 v[4:7], v[160:163], v[212:215], v[4:7]
	v_mfma_f32_16x16x32_bf16 v[0:3], v[174:177], v[212:215], v[0:3]
	v_mfma_f32_16x16x32_bf16 v[28:31], v[170:173], v[186:189], v[28:31]
	v_mfma_f32_16x16x32_bf16 v[24:27], v[178:181], v[186:189], v[24:27]
	v_mfma_f32_16x16x32_bf16 v[20:23], v[170:173], v[194:197], v[20:23]
	v_mfma_f32_16x16x32_bf16 v[16:19], v[178:181], v[194:197], v[16:19]
	v_mfma_f32_16x16x32_bf16 v[12:15], v[170:173], v[206:209], v[12:15]
	v_mfma_f32_16x16x32_bf16 v[8:11], v[178:181], v[206:209], v[8:11]
	v_mfma_f32_16x16x32_bf16 v[4:7], v[170:173], v[216:219], v[4:7]
	v_mfma_f32_16x16x32_bf16 v[0:3], v[178:181], v[216:219], v[0:3]
	s_setprio 0
	s_barrier
	s_add_i32 s34, 0, 0x18000
	v_add_u32_e32 v84, s34, v168
	s_add_i32 s73, 0, 0x1c000
	ds_read_b128 v[40:43], v84
	ds_read_b128 v[68:71], v84 offset:1024
	ds_read_b128 v[156:159], v84 offset:2048
	ds_read_b128 v[160:163], v84 offset:3072
	v_add_u32_e32 v84, s73, v168
	ds_read_b128 v[170:173], v84
	ds_read_b128 v[174:177], v84 offset:1024
	ds_read_b128 v[178:181], v84 offset:2048
	ds_read_b128 v[182:185], v84 offset:3072
	s_add_u32 s16, s16, 0x40000
	s_addc_u32 s17, s17, 0
	s_mov_b32 m0, s86
	v_lshl_add_u64 v[220:221], s[16:17], 0, v[144:145]
	ds_read_b128 v[84:87], v169 offset:32768
	ds_read_b128 v[186:189], v169 offset:33792
	ds_read_b128 v[190:193], v169 offset:34816
	ds_read_b128 v[194:197], v169 offset:35840
	ds_read_b128 v[202:205], v169 offset:36864
	ds_read_b128 v[206:209], v169 offset:37888
	ds_read_b128 v[212:215], v169 offset:38912
	ds_read_b128 v[216:219], v169 offset:39936
	s_mov_b32 m0, s84
	s_nop 0
	global_load_lds_dwordx4 v[210:211], off
	s_mov_b32 m0, s85
	s_nop 0
	global_load_lds_dwordx4 v[224:225], off
	s_mov_b32 m0, s86
	s_nop 0
	global_load_lds_dwordx4 v[220:221], off
	v_lshl_add_u64 v[220:221], s[16:17], 0, v[148:149]
	s_mov_b32 m0, s87
	s_nop 0
	global_load_lds_dwordx4 v[220:221], off
	s_waitcnt vmcnt(8)
	s_waitcnt lgkmcnt(0)
	s_barrier
; #define PG8_STAGE(bufoff, gbase, voff) do { _Pragma("unroll") for (int _i = 0; _i < 2; ++_i) \
;         __builtin_amdgcn_global_load_lds((const unsigned*)((const char*)(gbase) + (voff)[_i]), (PG8_LAS unsigned*)(lds + (bufoff) + ldsw + _i * 8192), 16, 0, 0); } while (0)
; #define PG8_LDA(dst, b, h) do { _Pragma("unroll") for (int m = 0; m < 4; ++m) _Pragma("unroll") for (int k = 0; k < 2; ++k) dst[m][k] = *(const PG8_LAS bf16x8*)(lds + PG8_SA(b, h) + aoff + m * 2048 + k * 1024); } while (0)
; #define PG8_LDB(dst, b, h) do { _Pragma("unroll") for (int n = 0; n < 2; ++n) _Pragma("unroll") for (int k = 0; k < 2; ++k) dst[n][k] = *(const PG8_LAS bf16x8*)(lds + PG8_SB(b, h) + boff + n * 2048 + k * 1024); } while (0)
; #define PG8_MMA(ai, bj, At, Bt) do { __builtin_amdgcn_s_setprio(1); _Pragma("unroll") for (int m = 0; m < 4; ++m) _Pragma("unroll") for (int n = 0; n < 2; ++n) _Pragma("unroll") for (int k = 0; k < 2; ++k) \
;         acc[ai][bj][m][n] = __builtin_amdgcn_mfma_f32_16x16x32_bf16(Bt[n][k], At[m][k], acc[ai][bj][m][n], 0, 0, 0); __builtin_amdgcn_s_setprio(0); } while (0)
; #define PG8_WAIT_V(n) asm volatile("s_waitcnt vmcnt(" #n ")" ::: "memory")
; #define PG8_WAIT_L(n) asm volatile("s_waitcnt lgkmcnt(" #n ")" ::: "memory")
; #define PG8_BAR __builtin_amdgcn_s_barrier()
; #define PG8_SCHED __builtin_amdgcn_sched_barrier(0)
; template <class Epi, class Sched, bool ALIGN_EPI = false, bool SP2 = false>
; __device__ __forceinline__ void gemm_phase(PG8_LAS unsigned char* lds, const Gemm g, const Sched& S, const Epi& E, const int wave_id) {
;     ...
;             PG8_LDB(B0, 1, 0); PG8_LDB(B1, 1, 1); PG8_SCHED; PG8_LDA(At, 1, 0); PG8_STAGE(PG8_SA(0, 1), a2 + hstep, voffA);
;             PG8_WAIT_V(8); PG8_WAIT_L(0); PG8_BAR; PG8_MMA(0, 0, At, B0); PG8_MMA(0, 1, At, B1); PG8_BAR; PG8_SCHED;
;             PG8_LDA(At, 1, 1); PG8_STAGE(PG8_SB(1, 0), b3, voffB); PG8_STAGE(PG8_SB(1, 1), b3 + hstep, voffB); PG8_STAGE(PG8_SA(1, 0), a3, voffA);
;             PG8_WAIT_V(8); PG8_WAIT_L(0); PG8_BAR; PG8_MMA(1, 0, At, B0); PG8_MMA(1, 1, At, B1); PG8_BAR; PG8_SCHED;
	s_setprio 1
	s_waitcnt lgkmcnt(0)
	v_mfma_f32_16x16x32_bf16 v[136:139], v[40:43], v[84:87], v[136:139]
	v_mfma_f32_16x16x32_bf16 v[132:135], v[156:159], v[84:87], v[132:135]
	v_mfma_f32_16x16x32_bf16 v[128:131], v[40:43], v[190:193], v[128:131]
	v_mfma_f32_16x16x32_bf16 v[124:127], v[156:159], v[190:193], v[124:127]
	v_mfma_f32_16x16x32_bf16 v[120:123], v[40:43], v[202:205], v[120:123]
	v_mfma_f32_16x16x32_bf16 v[116:119], v[156:159], v[202:205], v[116:119]
	v_mfma_f32_16x16x32_bf16 v[112:115], v[40:43], v[212:215], v[112:115]
	v_mfma_f32_16x16x32_bf16 v[104:107], v[156:159], v[212:215], v[104:107]
	v_mfma_f32_16x16x32_bf16 v[136:139], v[68:71], v[186:189], v[136:139]
	v_mfma_f32_16x16x32_bf16 v[132:135], v[160:163], v[186:189], v[132:135]
	v_mfma_f32_16x16x32_bf16 v[128:131], v[68:71], v[194:197], v[128:131]
	v_mfma_f32_16x16x32_bf16 v[124:127], v[160:163], v[194:197], v[124:127]
	v_mfma_f32_16x16x32_bf16 v[120:123], v[68:71], v[206:209], v[120:123]
	v_mfma_f32_16x16x32_bf16 v[116:119], v[160:163], v[206:209], v[116:119]
	v_mfma_f32_16x16x32_bf16 v[112:115], v[68:71], v[216:219], v[112:115]
	v_mfma_f32_16x16x32_bf16 v[104:107], v[160:163], v[216:219], v[104:107]
	s_setprio 0
	s_setprio 1
	v_mfma_f32_16x16x32_bf16 v[80:83], v[170:173], v[84:87], v[80:83]
	v_mfma_f32_16x16x32_bf16 v[76:79], v[178:181], v[84:87], v[76:79]
	v_mfma_f32_16x16x32_bf16 v[64:67], v[170:173], v[190:193], v[64:67]
	v_mfma_f32_16x16x32_bf16 v[60:63], v[178:181], v[190:193], v[60:63]
	v_mfma_f32_16x16x32_bf16 v[56:59], v[170:173], v[202:205], v[56:59]
	v_mfma_f32_16x16x32_bf16 v[52:55], v[178:181], v[202:205], v[52:55]
	v_mfma_f32_16x16x32_bf16 v[48:51], v[170:173], v[212:215], v[48:51]
	v_mfma_f32_16x16x32_bf16 v[44:47], v[178:181], v[212:215], v[44:47]
	v_mfma_f32_16x16x32_bf16 v[80:83], v[174:177], v[186:189], v[80:83]
	v_mfma_f32_16x16x32_bf16 v[76:79], v[182:185], v[186:189], v[76:79]
	v_mfma_f32_16x16x32_bf16 v[64:67], v[174:177], v[194:197], v[64:67]
	v_mfma_f32_16x16x32_bf16 v[60:63], v[182:185], v[194:197], v[60:63]
	v_mfma_f32_16x16x32_bf16 v[56:59], v[174:177], v[206:209], v[56:59]
	v_mfma_f32_16x16x32_bf16 v[52:55], v[182:185], v[206:209], v[52:55]
	v_mfma_f32_16x16x32_bf16 v[48:51], v[174:177], v[216:219], v[48:51]
	v_mfma_f32_16x16x32_bf16 v[44:47], v[182:185], v[216:219], v[44:47]
	s_setprio 0
	s_barrier
	s_add_i32 s16, s34, s25
	v_lshl_add_u64 v[84:85], v[164:165], 0, s[88:89]
	s_mov_b32 m0, s16
	ds_read_b128 v[186:189], v169 offset:49152
	ds_read_b128 v[190:193], v169 offset:50176
	ds_read_b128 v[194:197], v169 offset:51200
	ds_read_b128 v[202:205], v169 offset:52224
	ds_read_b128 v[206:209], v169 offset:53248
	ds_read_b128 v[212:215], v169 offset:54272
	ds_read_b128 v[216:219], v169 offset:55296
	ds_read_b128 v[220:223], v169 offset:56320
	global_load_lds_dwordx4 v[84:85], off
	s_add_i32 m0, s16, 0x2000
	s_add_u32 s14, s14, 0x40080
	v_lshl_add_u64 v[84:85], v[198:199], 0, s[88:89]
	s_addc_u32 s15, s15, 0
	s_add_i32 s16, s73, s25
	global_load_lds_dwordx4 v[84:85], off
	v_lshl_add_u64 v[84:85], s[14:15], 0, v[146:147]
	s_mov_b32 m0, s16
	s_nop 0
	global_load_lds_dwordx4 v[84:85], off
	v_lshl_add_u64 v[84:85], s[14:15], 0, v[150:151]
	s_add_i32 m0, s16, 0x2000
	s_nop 0
	global_load_lds_dwordx4 v[84:85], off
	s_waitcnt vmcnt(6)
	s_waitcnt lgkmcnt(0)
	s_barrier
	s_setprio 1
	s_waitcnt lgkmcnt(0)
	v_mfma_f32_16x16x32_bf16 v[84:87], v[40:43], v[186:189], v[108:111]
	v_mfma_f32_16x16x32_bf16 v[108:111], v[68:71], v[190:193], v[84:87]
	v_mfma_f32_16x16x32_bf16 v[84:87], v[156:159], v[186:189], v[96:99]
	v_mfma_f32_16x16x32_bf16 v[96:99], v[160:163], v[190:193], v[84:87]
	v_mfma_f32_16x16x32_bf16 v[84:87], v[40:43], v[194:197], v[100:103]
	v_mfma_f32_16x16x32_bf16 v[100:103], v[68:71], v[202:205], v[84:87]
	v_mfma_f32_16x16x32_bf16 v[84:87], v[156:159], v[194:197], v[88:91]
	v_mfma_f32_16x16x32_bf16 v[88:91], v[160:163], v[202:205], v[84:87]
	v_mfma_f32_16x16x32_bf16 v[84:87], v[40:43], v[206:209], v[92:95]
	v_mfma_f32_16x16x32_bf16 v[32:35], v[40:43], v[216:219], v[32:35]
	v_mfma_f32_16x16x32_bf16 v[92:95], v[68:71], v[212:215], v[84:87]
	v_mfma_f32_16x16x32_bf16 v[72:75], v[156:159], v[206:209], v[72:75]
	v_mfma_f32_16x16x32_bf16 v[84:87], v[68:71], v[220:223], v[32:35]
	v_mfma_f32_16x16x32_bf16 v[32:35], v[156:159], v[216:219], v[36:39]
	v_mfma_f32_16x16x32_bf16 v[72:75], v[160:163], v[212:215], v[72:75]
	v_mfma_f32_16x16x32_bf16 v[68:71], v[160:163], v[220:223], v[32:35]
	s_setprio 0
	s_setprio 1
	v_mfma_f32_16x16x32_bf16 v[28:31], v[170:173], v[186:189], v[28:31]
	v_mfma_f32_16x16x32_bf16 v[24:27], v[178:181], v[186:189], v[24:27]
	v_mfma_f32_16x16x32_bf16 v[20:23], v[170:173], v[194:197], v[20:23]
	v_mfma_f32_16x16x32_bf16 v[16:19], v[178:181], v[194:197], v[16:19]
	v_mfma_f32_16x16x32_bf16 v[12:15], v[170:173], v[206:209], v[12:15]
	v_mfma_f32_16x16x32_bf16 v[8:11], v[178:181], v[206:209], v[8:11]
	v_mfma_f32_16x16x32_bf16 v[4:7], v[170:173], v[216:219], v[4:7]
	v_mfma_f32_16x16x32_bf16 v[0:3], v[178:181], v[216:219], v[0:3]
	v_mfma_f32_16x16x32_bf16 v[28:31], v[174:177], v[190:193], v[28:31]
	v_mfma_f32_16x16x32_bf16 v[24:27], v[182:185], v[190:193], v[24:27]
	v_mfma_f32_16x16x32_bf16 v[20:23], v[174:177], v[202:205], v[20:23]
	v_mfma_f32_16x16x32_bf16 v[16:19], v[182:185], v[202:205], v[16:19]
	v_mfma_f32_16x16x32_bf16 v[12:15], v[174:177], v[212:215], v[12:15]
	v_mfma_f32_16x16x32_bf16 v[8:11], v[182:185], v[212:215], v[8:11]
	v_mfma_f32_16x16x32_bf16 v[4:7], v[174:177], v[220:223], v[4:7]
	v_mfma_f32_16x16x32_bf16 v[0:3], v[182:185], v[220:223], v[0:3]
	s_setprio 0
	s_barrier
	s_add_i32 s72, s72, 2
	s_add_u32 s12, s12, 0x100
	s_addc_u32 s13, s13, 0
	s_add_u32 s68, s68, 0x100
	s_addc_u32 s69, s69, 0
	s_cmp_gt_u32 s72, 13
	s_cbranch_scc0 .LBB0_695
	s_and_b64 vcc, exec, s[40:41]
	s_cbranch_vccz .LBB0_698
	s_barrier

; #define PG8_STAGE(bufoff, gbase, voff) do { _Pragma("unroll") for (int _i = 0; _i < 2; ++_i) \
;         __builtin_amdgcn_global_load_lds((const unsigned*)((const char*)(gbase) + (voff)[_i]), (PG8_LAS unsigned*)(lds + (bufoff) + ldsw + _i * 8192), 16, 0, 0); } while (0)
; #define PG8_WAIT_V(n) asm volatile("s_waitcnt vmcnt(" #n ")" ::: "memory")
; #define PG8_BAR __builtin_amdgcn_s_barrier()
; #define LAS __attribute__((address_space(3)))
; template <class Epi, class Sched, bool ALIGN_EPI = false, bool SP2 = false>
; __device__ __forceinline__ void gemm_phase(PG8_LAS unsigned char* lds, const Gemm g, const Sched& S, const Epi& E, const int wave_id) {
;     ...
;         PG8_STAGE(PG8_SB(0, 0), cB, voffB); PG8_STAGE(PG8_SB(0, 1), cB + hstep, voffB); PG8_STAGE(PG8_SA(0, 0), cA, voffA); PG8_STAGE(PG8_SA(0, 1), cA + hstep, voffA);
;         if (wr == 1) PG8_BAR;
;         PG8_WAIT_V(2); PG8_BAR;
;         PG8_STAGE(PG8_SB(1, 0), cB + kstep, voffB); PG8_STAGE(PG8_SA(1, 0), cA + kstep, voffA); PG8_STAGE(PG8_SB(1, 1), cB + hstep + kstep, voffB);
;         PG8_WAIT_V(6); PG8_BAR;
;     __device__ __forceinline__ void pre_finish(const f32x4 (&p)[4], const float (&c)[3], int tid) const {
;         if (tid < 256) { const f32x4 s4 = (p[0] + p[1]) + (p[2] + p[3]); ((LAS float*)rtab)[tid] = rsqrtf(((s4[0] + s4[1]) + (s4[2] + s4[3])) * (1.0f / D) + EPS); }
.LBB0_1019:
	v_mov_b32_e32 v135, v201
	v_lshl_add_u64 v[24:25], s[14:15], 0, v[134:135]
	v_mov_b32_e32 v139, v201
	v_lshl_add_u64 v[26:27], s[14:15], 0, v[138:139]
	v_mov_b32_e32 v133, v201
	s_add_i32 m0, s67, 0x18000
	v_lshl_add_u64 v[24:25], v[24:25], 0, s[88:89]
	v_lshl_add_u64 v[28:29], s[12:13], 0, v[132:133]
	v_mov_b32_e32 v137, v201
	s_waitcnt vmcnt(2)
	s_barrier
	global_load_lds_dwordx4 v[24:25], off
	v_lshl_add_u64 v[24:25], v[26:27], 0, s[88:89]
	s_add_i32 m0, s67, 0x1a000
	s_add_i32 s73, s67, 0x8000
	s_add_i32 s74, s67, 0xa000
	v_lshl_add_u64 v[30:31], s[12:13], 0, v[136:137]
	global_load_lds_dwordx4 v[24:25], off
	s_add_u32 s6, s14, 0x40080
	s_addc_u32 s7, s15, 0
	s_add_i32 m0, s67, 0x1c000
	v_lshl_add_u64 v[24:25], s[6:7], 0, v[134:135]
	global_load_lds_dwordx4 v[24:25], off
	v_lshl_add_u64 v[24:25], s[6:7], 0, v[138:139]
	s_add_i32 m0, s67, 0x1e000
	s_nop 0
	global_load_lds_dwordx4 v[24:25], off
	s_waitcnt vmcnt(4)
	s_barrier
	s_and_saveexec_b64 s[6:7], vcc
	s_cbranch_execz .LBB0_1021
	s_waitcnt vmcnt(0)
	v_pk_add_f32 v[8:9], v[8:9], v[12:13]
	v_pk_add_f32 v[10:11], v[10:11], v[14:15]
	v_pk_add_f32 v[0:1], v[0:1], v[4:5]
	v_pk_add_f32 v[2:3], v[2:3], v[6:7]
	v_pk_add_f32 v[0:1], v[0:1], v[8:9]
	v_pk_add_f32 v[2:3], v[2:3], v[10:11]
	s_mov_b32 s9, 0x800000
	v_pk_mov_b32 v[4:5], v[0:1], v[2:3] op_sel:[1,0]
	v_mov_b32_e32 v1, v3
	v_pk_add_f32 v[0:1], v[4:5], v[0:1]
	s_nop 0
	v_add_f32_e32 v0, v0, v1
	v_mov_b32_e32 v1, 0x358637bd
	v_fmamk_f32 v0, v0, 0x3a800000, v1
	v_mul_f32_e32 v1, 0x4b800000, v0
	v_cmp_gt_f32_e32 vcc, s9, v0
	s_nop 1
	v_cndmask_b32_e32 v0, v0, v1, vcc
	v_rsq_f32_e32 v0, v0
	s_nop 0
	v_mul_f32_e32 v1, 0x45800000, v0
	v_cndmask_b32_e32 v0, v0, v1, vcc
	v_lshl_add_u32 v1, v16, 2, 0
	v_add_u32_e32 v1, 0x22400, v1
	ds_write_b32 v1, v0

; #define PG8_STAGE(bufoff, gbase, voff) do { _Pragma("unroll") for (int _i = 0; _i < 2; ++_i) \
;         __builtin_amdgcn_global_load_lds((const unsigned*)((const char*)(gbase) + (voff)[_i]), (PG8_LAS unsigned*)(lds + (bufoff) + ldsw + _i * 8192), 16, 0, 0); } while (0)
; #define PG8_LDA(dst, b, h) do { _Pragma("unroll") for (int m = 0; m < 4; ++m) _Pragma("unroll") for (int k = 0; k < 2; ++k) dst[m][k] = *(const PG8_LAS bf16x8*)(lds + PG8_SA(b, h) + aoff + m * 2048 + k * 1024); } while (0)
; #define PG8_LDB(dst, b, h) do { _Pragma("unroll") for (int n = 0; n < 2; ++n) _Pragma("unroll") for (int k = 0; k < 2; ++k) dst[n][k] = *(const PG8_LAS bf16x8*)(lds + PG8_SB(b, h) + boff + n * 2048 + k * 1024); } while (0)
; #define PG8_MMA(ai, bj, At, Bt) do { __builtin_amdgcn_s_setprio(1); _Pragma("unroll") for (int m = 0; m < 4; ++m) _Pragma("unroll") for (int n = 0; n < 2; ++n) _Pragma("unroll") for (int k = 0; k < 2; ++k) \
;         acc[ai][bj][m][n] = __builtin_amdgcn_mfma_f32_16x16x32_bf16(Bt[n][k], At[m][k], acc[ai][bj][m][n], 0, 0, 0); __builtin_amdgcn_s_setprio(0); } while (0)
; #define PG8_WAIT_V(n) asm volatile("s_waitcnt vmcnt(" #n ")" ::: "memory")
; #define PG8_BAR __builtin_amdgcn_s_barrier()
; template <class Epi, class Sched, bool ALIGN_EPI = false, bool SP2 = false>
; __device__ __forceinline__ void gemm_phase(PG8_LAS unsigned char* lds, const Gemm g, const Sched& S, const Epi& E, const int wave_id) {
;     ...
;         for (int t = 0; t < nt; t += 2) {
;             const bool last = (t == nt - 2);
;             const char* a1 = cA + (size_t)(t + 1) * kstep;
;             const char* a2 = last ? nA : cA + (size_t)(t + 2) * kstep; const char* b2 = last ? nB : cB + (size_t)(t + 2) * kstep;
;             const char* a3 = a2 + kstep; const char* b3 = b2 + kstep;
;             if (last && has_next) S.a_ready(nxt);
;             if constexpr (SP2) {
;             PG8_LDB(B0, 0, 0); PG8_LDB(B1, 0, 1); PG8_SCHED; PG8_LDA(At, 0, 0); PG8_STAGE(PG8_SA(1, 1), a1 + hstep, voffA);
;             PG8_WAIT_V(8); PG8_WAIT_L(0); PG8_BAR; PG8_MMA(0, 0, At, B0); PG8_MMA(0, 1, At, B1); PG8_BAR; PG8_SCHED;
;             PG8_LDA(At, 0, 1); PG8_STAGE(PG8_SB(0, 0), b2, voffB); PG8_STAGE(PG8_SB(0, 1), b2 + hstep, voffB); PG8_STAGE(PG8_SA(0, 0), a2, voffA);
;             PG8_WAIT_V(8); PG8_WAIT_L(0); PG8_BAR; PG8_MMA(1, 0, At, B0); PG8_MMA(1, 1, At, B1); PG8_BAR; PG8_SCHED;
.LBB0_1027:
	s_add_u32 s14, s12, 0xfffc0080
	s_addc_u32 s15, s13, -1
	s_add_i32 s49, 0, 0x10000
	s_cmp_eq_u32 s48, 12
	s_cselect_b32 s17, s0, s15
	s_cselect_b32 s16, s1, s14
	v_add_u32_e32 v152, s49, v156
	s_cselect_b32 s15, s9, s43
	s_cselect_b32 s14, s11, s41
	s_add_i32 s52, 0, 0x14000
	ds_read_b128 v[144:147], v152
	ds_read_b128 v[148:151], v152 offset:1024
	ds_read_b128 v[158:161], v152 offset:2048
	ds_read_b128 v[162:165], v152 offset:3072
	v_add_u32_e32 v152, s52, v156
	ds_read_b128 v[166:169], v152
	ds_read_b128 v[170:173], v152 offset:1024
	ds_read_b128 v[174:177], v152 offset:2048
	ds_read_b128 v[178:181], v152 offset:3072
	ds_read_b128 v[182:185], v157
	ds_read_b128 v[186:189], v157 offset:1024
	ds_read_b128 v[190:193], v157 offset:2048
	ds_read_b128 v[194:197], v157 offset:3072
	ds_read_b128 v[202:205], v157 offset:4096
	ds_read_b128 v[212:215], v157 offset:5120
	ds_read_b128 v[216:219], v157 offset:6144
	ds_read_b128 v[220:223], v157 offset:7168
	s_add_u32 s50, s12, 0xfffc0000
	s_addc_u32 s51, s13, -1
	v_lshl_add_u64 v[152:153], s[50:51], 0, v[140:141]
	s_mov_b32 m0, s73
	s_nop 0
	global_load_lds_dwordx4 v[152:153], off
	v_lshl_add_u64 v[152:153], s[50:51], 0, v[142:143]
	s_mov_b32 m0, s74
	s_nop 0
	global_load_lds_dwordx4 v[152:153], off
	v_lshl_add_u64 v[152:153], s[12:13], 0, v[140:141]
	s_add_i32 m0, s67, 0xc000
	s_nop 0
	global_load_lds_dwordx4 v[152:153], off
	v_lshl_add_u64 v[152:153], s[12:13], 0, v[142:143]
	s_add_i32 m0, s67, 0xe000
	s_nop 0
	global_load_lds_dwordx4 v[152:153], off
	s_waitcnt vmcnt(8)
	s_waitcnt lgkmcnt(0)
	s_barrier
	s_setprio 1
	s_waitcnt lgkmcnt(0)
	v_mfma_f32_16x16x32_bf16 v[124:127], v[144:147], v[182:185], v[124:127]
	v_mfma_f32_16x16x32_bf16 v[120:123], v[158:161], v[182:185], v[120:123]
	v_mfma_f32_16x16x32_bf16 v[108:111], v[144:147], v[190:193], v[108:111]
	v_mfma_f32_16x16x32_bf16 v[104:107], v[158:161], v[190:193], v[104:107]
	v_mfma_f32_16x16x32_bf16 v[92:95], v[144:147], v[202:205], v[92:95]
	v_mfma_f32_16x16x32_bf16 v[88:91], v[158:161], v[202:205], v[88:91]
	v_mfma_f32_16x16x32_bf16 v[76:79], v[144:147], v[216:219], v[76:79]
	v_mfma_f32_16x16x32_bf16 v[72:75], v[158:161], v[216:219], v[72:75]
	v_mfma_f32_16x16x32_bf16 v[124:127], v[148:151], v[186:189], v[124:127]
	v_mfma_f32_16x16x32_bf16 v[120:123], v[162:165], v[186:189], v[120:123]
	v_mfma_f32_16x16x32_bf16 v[108:111], v[148:151], v[194:197], v[108:111]
	v_mfma_f32_16x16x32_bf16 v[104:107], v[162:165], v[194:197], v[104:107]
	v_mfma_f32_16x16x32_bf16 v[92:95], v[148:151], v[212:215], v[92:95]
	v_mfma_f32_16x16x32_bf16 v[88:91], v[162:165], v[212:215], v[88:91]
	v_mfma_f32_16x16x32_bf16 v[76:79], v[148:151], v[220:223], v[76:79]
	v_mfma_f32_16x16x32_bf16 v[72:75], v[162:165], v[220:223], v[72:75]
	s_setprio 0
	s_setprio 1
	v_mfma_f32_16x16x32_bf16 v[116:119], v[166:169], v[182:185], v[116:119]
	v_mfma_f32_16x16x32_bf16 v[112:115], v[174:177], v[182:185], v[112:115]
	v_mfma_f32_16x16x32_bf16 v[100:103], v[166:169], v[190:193], v[100:103]
	v_mfma_f32_16x16x32_bf16 v[96:99], v[174:177], v[190:193], v[96:99]
	v_mfma_f32_16x16x32_bf16 v[84:87], v[166:169], v[202:205], v[84:87]
	v_mfma_f32_16x16x32_bf16 v[80:83], v[174:177], v[202:205], v[80:83]
	v_mfma_f32_16x16x32_bf16 v[68:71], v[166:169], v[216:219], v[68:71]
	v_mfma_f32_16x16x32_bf16 v[64:67], v[174:177], v[216:219], v[64:67]
	v_mfma_f32_16x16x32_bf16 v[116:119], v[170:173], v[186:189], v[116:119]
	v_mfma_f32_16x16x32_bf16 v[112:115], v[178:181], v[186:189], v[112:115]
	v_mfma_f32_16x16x32_bf16 v[100:103], v[170:173], v[194:197], v[100:103]
	v_mfma_f32_16x16x32_bf16 v[96:99], v[178:181], v[194:197], v[96:99]
	v_mfma_f32_16x16x32_bf16 v[84:87], v[170:173], v[212:215], v[84:87]
	v_mfma_f32_16x16x32_bf16 v[80:83], v[178:181], v[212:215], v[80:83]
	v_mfma_f32_16x16x32_bf16 v[68:71], v[170:173], v[220:223], v[68:71]
	v_mfma_f32_16x16x32_bf16 v[64:67], v[178:181], v[220:223], v[64:67]
	s_setprio 0
	s_barrier
	s_add_i32 s49, s49, s27
	v_lshl_add_u64 v[152:153], s[14:15], 0, v[134:135]
	s_mov_b32 m0, s49
	ds_read_b128 v[182:185], v157 offset:16384
	ds_read_b128 v[186:189], v157 offset:17408
	ds_read_b128 v[190:193], v157 offset:18432
	ds_read_b128 v[194:197], v157 offset:19456
	ds_read_b128 v[202:205], v157 offset:20480
	ds_read_b128 v[212:215], v157 offset:21504
	ds_read_b128 v[216:219], v157 offset:22528
	ds_read_b128 v[220:223], v157 offset:23552
	global_load_lds_dwordx4 v[152:153], off
	s_add_i32 m0, s49, 0x2000
	s_add_u32 s50, s14, 0x40000
	v_lshl_add_u64 v[198:199], s[14:15], 0, v[138:139]
	s_addc_u32 s51, s15, 0
	s_add_i32 s49, s52, s27
	global_load_lds_dwordx4 v[198:199], off
	v_lshl_add_u64 v[206:207], s[50:51], 0, v[134:135]
	s_mov_b32 m0, s49
	v_lshl_add_u64 v[208:209], s[16:17], 0, v[136:137]
	global_load_lds_dwordx4 v[206:207], off
	v_lshl_add_u64 v[206:207], s[50:51], 0, v[138:139]
	s_add_i32 m0, s49, 0x2000
	s_nop 0
	global_load_lds_dwordx4 v[206:207], off
	v_lshl_add_u64 v[206:207], s[16:17], 0, v[132:133]
	s_waitcnt vmcnt(6)
	s_waitcnt lgkmcnt(0)
	s_barrier
; #define PG8_STAGE(bufoff, gbase, voff) do { _Pragma("unroll") for (int _i = 0; _i < 2; ++_i) \
;         __builtin_amdgcn_global_load_lds((const unsigned*)((const char*)(gbase) + (voff)[_i]), (PG8_LAS unsigned*)(lds + (bufoff) + ldsw + _i * 8192), 16, 0, 0); } while (0)
; #define PG8_LDA(dst, b, h) do { _Pragma("unroll") for (int m = 0; m < 4; ++m) _Pragma("unroll") for (int k = 0; k < 2; ++k) dst[m][k] = *(const PG8_LAS bf16x8*)(lds + PG8_SA(b, h) + aoff + m * 2048 + k * 1024); } while (0)
; #define PG8_LDB(dst, b, h) do { _Pragma("unroll") for (int n = 0; n < 2; ++n) _Pragma("unroll") for (int k = 0; k < 2; ++k) dst[n][k] = *(const PG8_LAS bf16x8*)(lds + PG8_SB(b, h) + boff + n * 2048 + k * 1024); } while (0)
; #define PG8_MMA(ai, bj, At, Bt) do { __builtin_amdgcn_s_setprio(1); _Pragma("unroll") for (int m = 0; m < 4; ++m) _Pragma("unroll") for (int n = 0; n < 2; ++n) _Pragma("unroll") for (int k = 0; k < 2; ++k) \
;         acc[ai][bj][m][n] = __builtin_amdgcn_mfma_f32_16x16x32_bf16(Bt[n][k], At[m][k], acc[ai][bj][m][n], 0, 0, 0); __builtin_amdgcn_s_setprio(0); } while (0)
; #define PG8_WAIT_V(n) asm volatile("s_waitcnt vmcnt(" #n ")" ::: "memory")
; #define PG8_WAIT_L(n) asm volatile("s_waitcnt lgkmcnt(" #n ")" ::: "memory")
; #define PG8_BAR __builtin_amdgcn_s_barrier()
; #define PG8_SCHED __builtin_amdgcn_sched_barrier(0)
; template <class Epi, class Sched, bool ALIGN_EPI = false, bool SP2 = false>
; __device__ __forceinline__ void gemm_phase(PG8_LAS unsigned char* lds, const Gemm g, const Sched& S, const Epi& E, const int wave_id) {
;     ...
;             PG8_WAIT_V(8); PG8_WAIT_L(0); PG8_BAR; PG8_MMA(0, 0, At, B0); PG8_MMA(0, 1, At, B1); PG8_BAR; PG8_SCHED;
;             PG8_LDA(At, 0, 1); PG8_STAGE(PG8_SB(0, 0), b2, voffB); PG8_STAGE(PG8_SB(0, 1), b2 + hstep, voffB); PG8_STAGE(PG8_SA(0, 0), a2, voffA);
;             PG8_WAIT_V(8); PG8_WAIT_L(0); PG8_BAR; PG8_MMA(1, 0, At, B0); PG8_MMA(1, 1, At, B1); PG8_BAR; PG8_SCHED;
;             PG8_LDB(B0, 1, 0); PG8_LDB(B1, 1, 1); PG8_SCHED; PG8_LDA(At, 1, 0); PG8_STAGE(PG8_SA(0, 1), a2 + hstep, voffA);
;             PG8_WAIT_V(8); PG8_WAIT_L(0); PG8_BAR; PG8_MMA(0, 0, At, B0); PG8_MMA(0, 1, At, B1); PG8_BAR; PG8_SCHED;
	s_setprio 1
	s_waitcnt lgkmcnt(0)
	v_mfma_f32_16x16x32_bf16 v[60:63], v[144:147], v[182:185], v[60:63]
	v_mfma_f32_16x16x32_bf16 v[56:59], v[158:161], v[182:185], v[56:59]
	v_mfma_f32_16x16x32_bf16 v[44:47], v[144:147], v[190:193], v[44:47]
	v_mfma_f32_16x16x32_bf16 v[40:43], v[158:161], v[190:193], v[40:43]
	v_mfma_f32_16x16x32_bf16 v[28:31], v[144:147], v[202:205], v[28:31]
	v_mfma_f32_16x16x32_bf16 v[24:27], v[158:161], v[202:205], v[24:27]
	v_mfma_f32_16x16x32_bf16 v[12:15], v[144:147], v[216:219], v[12:15]
	v_mfma_f32_16x16x32_bf16 v[8:11], v[158:161], v[216:219], v[8:11]
	v_mfma_f32_16x16x32_bf16 v[60:63], v[148:151], v[186:189], v[60:63]
	v_mfma_f32_16x16x32_bf16 v[56:59], v[162:165], v[186:189], v[56:59]
	v_mfma_f32_16x16x32_bf16 v[44:47], v[148:151], v[194:197], v[44:47]
	v_mfma_f32_16x16x32_bf16 v[40:43], v[162:165], v[194:197], v[40:43]
	v_mfma_f32_16x16x32_bf16 v[28:31], v[148:151], v[212:215], v[28:31]
	v_mfma_f32_16x16x32_bf16 v[24:27], v[162:165], v[212:215], v[24:27]
	v_mfma_f32_16x16x32_bf16 v[12:15], v[148:151], v[220:223], v[12:15]
	v_mfma_f32_16x16x32_bf16 v[8:11], v[162:165], v[220:223], v[8:11]
	s_setprio 0
	s_setprio 1
	v_mfma_f32_16x16x32_bf16 v[52:55], v[166:169], v[182:185], v[52:55]
	v_mfma_f32_16x16x32_bf16 v[48:51], v[174:177], v[182:185], v[48:51]
	v_mfma_f32_16x16x32_bf16 v[36:39], v[166:169], v[190:193], v[36:39]
	v_mfma_f32_16x16x32_bf16 v[32:35], v[174:177], v[190:193], v[32:35]
	v_mfma_f32_16x16x32_bf16 v[20:23], v[166:169], v[202:205], v[20:23]
	v_mfma_f32_16x16x32_bf16 v[16:19], v[174:177], v[202:205], v[16:19]
	v_mfma_f32_16x16x32_bf16 v[4:7], v[166:169], v[216:219], v[4:7]
	v_mfma_f32_16x16x32_bf16 v[0:3], v[174:177], v[216:219], v[0:3]
	v_mfma_f32_16x16x32_bf16 v[52:55], v[170:173], v[186:189], v[52:55]
	v_mfma_f32_16x16x32_bf16 v[48:51], v[178:181], v[186:189], v[48:51]
	v_mfma_f32_16x16x32_bf16 v[36:39], v[170:173], v[194:197], v[36:39]
	v_mfma_f32_16x16x32_bf16 v[32:35], v[178:181], v[194:197], v[32:35]
	v_mfma_f32_16x16x32_bf16 v[20:23], v[170:173], v[212:215], v[20:23]
	v_mfma_f32_16x16x32_bf16 v[16:19], v[178:181], v[212:215], v[16:19]
	v_mfma_f32_16x16x32_bf16 v[4:7], v[170:173], v[220:223], v[4:7]
	v_mfma_f32_16x16x32_bf16 v[0:3], v[178:181], v[220:223], v[0:3]
	s_setprio 0
	s_barrier
	s_add_i32 s49, 0, 0x18000
	s_add_i32 s50, 0, 0x1c000
	v_add_u32_e32 v162, s49, v156
	v_add_u32_e32 v178, s50, v156
	ds_read_b128 v[144:147], v162
	ds_read_b128 v[148:151], v162 offset:1024
	ds_read_b128 v[158:161], v162 offset:2048
	ds_read_b128 v[162:165], v162 offset:3072
	ds_read_b128 v[166:169], v178
	ds_read_b128 v[170:173], v178 offset:1024
	ds_read_b128 v[174:177], v178 offset:2048
	ds_read_b128 v[178:181], v178 offset:3072
	s_add_u32 s16, s16, 0x40000
	s_addc_u32 s17, s17, 0
	s_mov_b32 m0, s69
	v_lshl_add_u64 v[210:211], s[16:17], 0, v[132:133]
	ds_read_b128 v[182:185], v157 offset:32768
	ds_read_b128 v[186:189], v157 offset:33792
	ds_read_b128 v[190:193], v157 offset:34816
	ds_read_b128 v[194:197], v157 offset:35840
	ds_read_b128 v[202:205], v157 offset:36864
	ds_read_b128 v[212:215], v157 offset:37888
	ds_read_b128 v[216:219], v157 offset:38912
	ds_read_b128 v[220:223], v157 offset:39936
	s_mov_b32 m0, s67
	s_nop 0
	global_load_lds_dwordx4 v[206:207], off
	s_mov_b32 m0, s68
	s_nop 0
	global_load_lds_dwordx4 v[208:209], off
	s_mov_b32 m0, s69
	s_nop 0
	global_load_lds_dwordx4 v[210:211], off
	v_lshl_add_u64 v[210:211], s[16:17], 0, v[136:137]
	s_mov_b32 m0, s72
	s_nop 0
	global_load_lds_dwordx4 v[210:211], off
	s_waitcnt vmcnt(8)
	s_waitcnt lgkmcnt(0)
	s_barrier
; #define PG8_STAGE(bufoff, gbase, voff) do { _Pragma("unroll") for (int _i = 0; _i < 2; ++_i) \
;         __builtin_amdgcn_global_load_lds((const unsigned*)((const char*)(gbase) + (voff)[_i]), (PG8_LAS unsigned*)(lds + (bufoff) + ldsw + _i * 8192), 16, 0, 0); } while (0)
; #define PG8_LDA(dst, b, h) do { _Pragma("unroll") for (int m = 0; m < 4; ++m) _Pragma("unroll") for (int k = 0; k < 2; ++k) dst[m][k] = *(const PG8_LAS bf16x8*)(lds + PG8_SA(b, h) + aoff + m * 2048 + k * 1024); } while (0)
; #define PG8_LDB(dst, b, h) do { _Pragma("unroll") for (int n = 0; n < 2; ++n) _Pragma("unroll") for (int k = 0; k < 2; ++k) dst[n][k] = *(const PG8_LAS bf16x8*)(lds + PG8_SB(b, h) + boff + n * 2048 + k * 1024); } while (0)
; #define PG8_MMA(ai, bj, At, Bt) do { __builtin_amdgcn_s_setprio(1); _Pragma("unroll") for (int m = 0; m < 4; ++m) _Pragma("unroll") for (int n = 0; n < 2; ++n) _Pragma("unroll") for (int k = 0; k < 2; ++k) \
;         acc[ai][bj][m][n] = __builtin_amdgcn_mfma_f32_16x16x32_bf16(Bt[n][k], At[m][k], acc[ai][bj][m][n], 0, 0, 0); __builtin_amdgcn_s_setprio(0); } while (0)
; #define PG8_WAIT_V(n) asm volatile("s_waitcnt vmcnt(" #n ")" ::: "memory")
; #define PG8_WAIT_L(n) asm volatile("s_waitcnt lgkmcnt(" #n ")" ::: "memory")
; #define PG8_BAR __builtin_amdgcn_s_barrier()
; #define PG8_SCHED __builtin_amdgcn_sched_barrier(0)
; template <class Epi, class Sched, bool ALIGN_EPI = false, bool SP2 = false>
; __device__ __forceinline__ void gemm_phase(PG8_LAS unsigned char* lds, const Gemm g, const Sched& S, const Epi& E, const int wave_id) {
;     ...
;             PG8_LDB(B0, 1, 0); PG8_LDB(B1, 1, 1); PG8_SCHED; PG8_LDA(At, 1, 0); PG8_STAGE(PG8_SA(0, 1), a2 + hstep, voffA);
;             PG8_WAIT_V(8); PG8_WAIT_L(0); PG8_BAR; PG8_MMA(0, 0, At, B0); PG8_MMA(0, 1, At, B1); PG8_BAR; PG8_SCHED;
;             PG8_LDA(At, 1, 1); PG8_STAGE(PG8_SB(1, 0), b3, voffB); PG8_STAGE(PG8_SB(1, 1), b3 + hstep, voffB); PG8_STAGE(PG8_SA(1, 0), a3, voffA);
;             PG8_WAIT_V(8); PG8_WAIT_L(0); PG8_BAR; PG8_MMA(1, 0, At, B0); PG8_MMA(1, 1, At, B1); PG8_BAR; PG8_SCHED;
	s_setprio 1
	s_waitcnt lgkmcnt(0)
	v_mfma_f32_16x16x32_bf16 v[124:127], v[144:147], v[182:185], v[124:127]
	v_mfma_f32_16x16x32_bf16 v[120:123], v[158:161], v[182:185], v[120:123]
	v_mfma_f32_16x16x32_bf16 v[108:111], v[144:147], v[190:193], v[108:111]
	v_mfma_f32_16x16x32_bf16 v[104:107], v[158:161], v[190:193], v[104:107]
	v_mfma_f32_16x16x32_bf16 v[92:95], v[144:147], v[202:205], v[92:95]
	v_mfma_f32_16x16x32_bf16 v[88:91], v[158:161], v[202:205], v[88:91]
	v_mfma_f32_16x16x32_bf16 v[76:79], v[144:147], v[216:219], v[76:79]
	v_mfma_f32_16x16x32_bf16 v[72:75], v[158:161], v[216:219], v[72:75]
	v_mfma_f32_16x16x32_bf16 v[124:127], v[148:151], v[186:189], v[124:127]
	v_mfma_f32_16x16x32_bf16 v[120:123], v[162:165], v[186:189], v[120:123]
	v_mfma_f32_16x16x32_bf16 v[108:111], v[148:151], v[194:197], v[108:111]
	v_mfma_f32_16x16x32_bf16 v[104:107], v[162:165], v[194:197], v[104:107]
	v_mfma_f32_16x16x32_bf16 v[92:95], v[148:151], v[212:215], v[92:95]
	v_mfma_f32_16x16x32_bf16 v[88:91], v[162:165], v[212:215], v[88:91]
	v_mfma_f32_16x16x32_bf16 v[76:79], v[148:151], v[220:223], v[76:79]
	v_mfma_f32_16x16x32_bf16 v[72:75], v[162:165], v[220:223], v[72:75]
	s_setprio 0
	s_setprio 1
	v_mfma_f32_16x16x32_bf16 v[116:119], v[166:169], v[182:185], v[116:119]
	v_mfma_f32_16x16x32_bf16 v[112:115], v[174:177], v[182:185], v[112:115]
	v_mfma_f32_16x16x32_bf16 v[100:103], v[166:169], v[190:193], v[100:103]
	v_mfma_f32_16x16x32_bf16 v[96:99], v[174:177], v[190:193], v[96:99]
	v_mfma_f32_16x16x32_bf16 v[84:87], v[166:169], v[202:205], v[84:87]
	v_mfma_f32_16x16x32_bf16 v[80:83], v[174:177], v[202:205], v[80:83]
	v_mfma_f32_16x16x32_bf16 v[68:71], v[166:169], v[216:219], v[68:71]
	v_mfma_f32_16x16x32_bf16 v[64:67], v[174:177], v[216:219], v[64:67]
	v_mfma_f32_16x16x32_bf16 v[116:119], v[170:173], v[186:189], v[116:119]
	v_mfma_f32_16x16x32_bf16 v[112:115], v[178:181], v[186:189], v[112:115]
	v_mfma_f32_16x16x32_bf16 v[100:103], v[170:173], v[194:197], v[100:103]
	v_mfma_f32_16x16x32_bf16 v[96:99], v[178:181], v[194:197], v[96:99]
	v_mfma_f32_16x16x32_bf16 v[84:87], v[170:173], v[212:215], v[84:87]
	v_mfma_f32_16x16x32_bf16 v[80:83], v[178:181], v[212:215], v[80:83]
	v_mfma_f32_16x16x32_bf16 v[68:71], v[170:173], v[220:223], v[68:71]
	v_mfma_f32_16x16x32_bf16 v[64:67], v[178:181], v[220:223], v[64:67]
	s_setprio 0
	s_barrier
	s_add_i32 s16, s49, s27
	v_lshl_add_u64 v[152:153], v[152:153], 0, s[88:89]
	s_mov_b32 m0, s16
	ds_read_b128 v[182:185], v157 offset:49152
	ds_read_b128 v[186:189], v157 offset:50176
	ds_read_b128 v[190:193], v157 offset:51200
	ds_read_b128 v[194:197], v157 offset:52224
	ds_read_b128 v[202:205], v157 offset:53248
	ds_read_b128 v[212:215], v157 offset:54272
	ds_read_b128 v[216:219], v157 offset:55296
	ds_read_b128 v[220:223], v157 offset:56320
	global_load_lds_dwordx4 v[152:153], off
	s_add_i32 m0, s16, 0x2000
	s_add_u32 s14, s14, 0x40080
	v_lshl_add_u64 v[152:153], v[198:199], 0, s[88:89]
	s_addc_u32 s15, s15, 0
	s_add_i32 s16, s50, s27
	global_load_lds_dwordx4 v[152:153], off
	v_lshl_add_u64 v[152:153], s[14:15], 0, v[134:135]
	s_mov_b32 m0, s16
	s_nop 0
	global_load_lds_dwordx4 v[152:153], off
	v_lshl_add_u64 v[152:153], s[14:15], 0, v[138:139]
	s_add_i32 m0, s16, 0x2000
	s_nop 0
	global_load_lds_dwordx4 v[152:153], off
	s_waitcnt vmcnt(6)
	s_waitcnt lgkmcnt(0)
	s_barrier
	s_setprio 1
	s_waitcnt lgkmcnt(0)
	v_mfma_f32_16x16x32_bf16 v[60:63], v[144:147], v[182:185], v[60:63]
	v_mfma_f32_16x16x32_bf16 v[56:59], v[158:161], v[182:185], v[56:59]
	v_mfma_f32_16x16x32_bf16 v[44:47], v[144:147], v[190:193], v[44:47]
	v_mfma_f32_16x16x32_bf16 v[40:43], v[158:161], v[190:193], v[40:43]
	v_mfma_f32_16x16x32_bf16 v[28:31], v[144:147], v[202:205], v[28:31]
	v_mfma_f32_16x16x32_bf16 v[24:27], v[158:161], v[202:205], v[24:27]
	v_mfma_f32_16x16x32_bf16 v[12:15], v[144:147], v[216:219], v[12:15]
	v_mfma_f32_16x16x32_bf16 v[8:11], v[158:161], v[216:219], v[8:11]
	v_mfma_f32_16x16x32_bf16 v[60:63], v[148:151], v[186:189], v[60:63]
	v_mfma_f32_16x16x32_bf16 v[56:59], v[162:165], v[186:189], v[56:59]
	v_mfma_f32_16x16x32_bf16 v[44:47], v[148:151], v[194:197], v[44:47]
	v_mfma_f32_16x16x32_bf16 v[40:43], v[162:165], v[194:197], v[40:43]
	v_mfma_f32_16x16x32_bf16 v[28:31], v[148:151], v[212:215], v[28:31]
	v_mfma_f32_16x16x32_bf16 v[24:27], v[162:165], v[212:215], v[24:27]
	v_mfma_f32_16x16x32_bf16 v[12:15], v[148:151], v[220:223], v[12:15]
	v_mfma_f32_16x16x32_bf16 v[8:11], v[162:165], v[220:223], v[8:11]
	s_setprio 0
	s_setprio 1
	v_mfma_f32_16x16x32_bf16 v[52:55], v[166:169], v[182:185], v[52:55]
	v_mfma_f32_16x16x32_bf16 v[48:51], v[174:177], v[182:185], v[48:51]
	v_mfma_f32_16x16x32_bf16 v[36:39], v[166:169], v[190:193], v[36:39]
	v_mfma_f32_16x16x32_bf16 v[32:35], v[174:177], v[190:193], v[32:35]
	v_mfma_f32_16x16x32_bf16 v[20:23], v[166:169], v[202:205], v[20:23]
	v_mfma_f32_16x16x32_bf16 v[16:19], v[174:177], v[202:205], v[16:19]
	v_mfma_f32_16x16x32_bf16 v[4:7], v[166:169], v[216:219], v[4:7]
	v_mfma_f32_16x16x32_bf16 v[0:3], v[174:177], v[216:219], v[0:3]
	v_mfma_f32_16x16x32_bf16 v[52:55], v[170:173], v[186:189], v[52:55]
	v_mfma_f32_16x16x32_bf16 v[48:51], v[178:181], v[186:189], v[48:51]
	v_mfma_f32_16x16x32_bf16 v[36:39], v[170:173], v[194:197], v[36:39]
	v_mfma_f32_16x16x32_bf16 v[32:35], v[178:181], v[194:197], v[32:35]
	v_mfma_f32_16x16x32_bf16 v[20:23], v[170:173], v[212:215], v[20:23]
	v_mfma_f32_16x16x32_bf16 v[16:19], v[178:181], v[212:215], v[16:19]
	v_mfma_f32_16x16x32_bf16 v[4:7], v[170:173], v[220:223], v[4:7]
	v_mfma_f32_16x16x32_bf16 v[0:3], v[178:181], v[220:223], v[0:3]
	s_setprio 0
	s_barrier
	s_add_i32 s48, s48, 2
	s_add_u32 s12, s12, 0x100
	s_addc_u32 s13, s13, 0
	s_add_u32 s41, s41, 0x100
	s_addc_u32 s43, s43, 0
	s_cmp_gt_u32 s48, 13
	s_cbranch_scc0 .LBB0_1027
	s_and_b64 vcc, exec, s[38:39]
	s_cbranch_vccz .LBB0_1030
	s_barrier
